# v7 + hand-scheduled pre-norm (phase_prep) loops: all loads up front, mods cached in regs, DPP reduction, next-row prefetch (tail prep and prep0)
# speedup vs baseline: 1.0504x; 1.0027x over previous
.LBB0_146:
	s_or_b64 exec, exec, s[0:1]
	v_readlane_b32 s8, v183, 1
	v_readlane_b32 s22, v183, 15
	v_readlane_b32 s0, v183, 0
	v_mov_b32_e32 v6, v104
	v_readlane_b32 s23, v183, 16
	s_add_u32 s6, s22, 0x4000000
	s_waitcnt lgkmcnt(0)
	s_barrier
	s_addc_u32 s7, s23, 0
	v_ashrrev_i32_e32 v4, 6, v6
	s_lshl_b32 s8, s0, 2
	v_add_u32_e32 v21, s8, v4
	s_movk_i32 s0, 0x4200
	v_writelane_b32 v182, s6, 1
	v_cmp_gt_i32_e32 vcc, s0, v21
	v_mbcnt_lo_u32_b32 v20, -1, 0
	v_readlane_b32 s9, v183, 2
	v_readlane_b32 s10, v183, 3
	v_readlane_b32 s11, v183, 4
	v_readlane_b32 s12, v183, 5
	v_readlane_b32 s13, v183, 6
	v_readlane_b32 s14, v183, 7
	v_readlane_b32 s15, v183, 8
	v_readlane_b32 s16, v183, 9
	v_readlane_b32 s17, v183, 10
	v_readlane_b32 s18, v183, 11
	v_readlane_b32 s19, v183, 12
	v_readlane_b32 s20, v183, 13
	v_readlane_b32 s21, v183, 14
	v_writelane_b32 v182, s7, 2
	s_and_saveexec_b64 s[0:1], vcc
	s_cbranch_execz .LBB0_153
	v_lshlrev_b32_e32 v0, 2, v6
	v_and_b32_e32 v8, 0xfc, v0
	v_mbcnt_hi_u32_b32 v0, -1, v20
	v_and_b32_e32 v2, 64, v0
	v_add_u32_e32 v2, 64, v2
	v_xor_b32_e32 v3, 32, v0
	v_cmp_lt_i32_e32 vcc, v3, v2
	v_ashrrev_i32_e32 v5, 31, v4
	s_ashr_i32 s9, s8, 31
	v_cndmask_b32_e32 v3, v0, v3, vcc
	v_lshlrev_b32_e32 v22, 2, v3
	v_xor_b32_e32 v3, 16, v0
	v_cmp_lt_i32_e32 vcc, v3, v2
	v_lshl_add_u64 v[4:5], v[4:5], 0, s[8:9]
	v_lshlrev_b64 v[4:5], 11, v[4:5]
	v_cndmask_b32_e32 v3, v0, v3, vcc
	v_lshlrev_b32_e32 v23, 2, v3
	v_xor_b32_e32 v3, 8, v0
	v_cmp_lt_i32_e32 vcc, v3, v2
	v_and_b32_e32 v6, 63, v6
	v_readlane_b32 s8, v183, 1
	v_cndmask_b32_e32 v3, v0, v3, vcc
	v_lshlrev_b32_e32 v24, 2, v3
	v_xor_b32_e32 v3, 4, v0
	v_cmp_lt_i32_e32 vcc, v3, v2
	v_mov_b32_e32 v1, 0
	s_lshl_b32 s6, s84, 2
	v_cndmask_b32_e32 v3, v0, v3, vcc
	v_lshlrev_b32_e32 v25, 2, v3
	v_xor_b32_e32 v3, 2, v0
	v_cmp_lt_i32_e32 vcc, v3, v2
	v_lshl_or_b32 v4, v6, 3, v4
	v_readlane_b32 s9, v183, 2
	v_cndmask_b32_e32 v3, v0, v3, vcc
	v_lshlrev_b32_e32 v26, 2, v3
	v_xor_b32_e32 v3, 1, v0
	v_cmp_lt_i32_e32 vcc, v3, v2
	v_readlane_b32 s22, v183, 15
	v_readlane_b32 s23, v183, 16
	v_cndmask_b32_e32 v0, v0, v3, vcc
	v_lshlrev_b32_e32 v27, 2, v0
	v_lshlrev_b32_e32 v0, 2, v8
	v_lshl_add_u64 v[2:3], s[80:81], 0, v[0:1]
	v_or_b32_e32 v0, 0x100, v8
	v_or_b32_e32 v10, 0x200, v8
	v_or_b32_e32 v12, 0x300, v8
	v_readlane_b32 s10, v183, 3
	v_readlane_b32 s11, v183, 4
	v_readlane_b32 s12, v183, 5
	v_readlane_b32 s13, v183, 6
	v_readlane_b32 s16, v183, 9
	v_readlane_b32 s17, v183, 10
	v_lshl_add_u64 v[4:5], s[22:23], 0, v[4:5]
	s_mov_b64 s[8:9], 0x5000400
	s_ashr_i32 s7, s6, 31
	v_lshl_add_u64 v[4:5], v[4:5], 0, s[8:9]
	s_lshl_b64 s[8:9], s[6:7], 11
	s_mov_b64 s[10:11], 0
	s_movk_i32 s7, 0x3fff
	v_lshlrev_b32_e32 v6, 2, v8
	s_mov_b64 s[12:13], 0x1000
	v_lshlrev_b32_e32 v8, 2, v0
	v_lshlrev_b32_e32 v10, 2, v10
	v_lshlrev_b32_e32 v12, 2, v12
	v_mov_b32_e32 v28, 0x358637bd
	s_mov_b32 s16, 0x800000
	s_movk_i32 s17, 0x41ff
	v_mov_b32_e32 v7, v1
	v_mov_b32_e32 v9, v1
	v_mov_b32_e32 v11, v1
	v_mov_b32_e32 v13, v1
	v_readlane_b32 s14, v183, 7
	v_readlane_b32 s15, v183, 8
	v_readlane_b32 s18, v183, 11
	v_readlane_b32 s19, v183, 12
	v_readlane_b32 s20, v183, 13
	v_readlane_b32 s21, v183, 14
	v_mov_b32_e32 v66, v28
	v_readlane_b32 s14, v182, 1
	v_readlane_b32 s15, v182, 2
	v_mov_b32_e32 v67, v6
	v_mov_b32_e32 v70, v4
	v_mov_b32_e32 v71, v5
	global_load_dwordx4 v[72:75], v[2:3], off
	global_load_dwordx4 v[76:79], v[2:3], off offset:1024
	global_load_dwordx4 v[80:83], v[2:3], off offset:2048
	global_load_dwordx4 v[84:87], v[2:3], off offset:3072
	v_mov_b32_e32 v68, -1
	v_and_b32_e32 v59, 0xffffff80, v21
	v_and_b32_e32 v61, 0x7f, v21
	v_cmp_lt_i32_e32 vcc, 0x3fff, v59
	v_lshrrev_b32_e32 v62, 13, v59
	v_and_b32_e32 v63, 0x1fff, v59
	v_add_u32_e32 v62, 0, v62
	v_lshl_or_b32 v63, v62, 13, v63
	v_add_u32_e32 v64, 0xffffc000, v21
	v_lshrrev_b32_e32 v64, 8, v64
	v_add_u32_e32 v64, 0, v64
	v_lshlrev_b32_e32 v64, 8, v64
	v_and_b32_e32 v56, 0x80, v21
	v_or_b32_e32 v64, v64, v56
	v_cndmask_b32_e32 v63, v63, v64, vcc
	v_mov_b32_e32 v56, 4
	v_cndmask_b32_e32 v62, v62, v56, vcc
	v_add_u32_e32 v63, v63, v61
	v_lshl_add_u32 v60, v63, 12, v67
	v_add_u32_e32 v62, 0, v62
	v_mul_u32_u24_e32 v62, 0x3000, v62
	v_add_u32_e32 v65, v62, v67
	s_cbranch_vccnz .LprepZ_ctx0
	global_load_dwordx4 v[0:3], v60, s[68:69]
	global_load_dwordx4 v[4:7], v60, s[68:69] offset:1024
	global_load_dwordx4 v[8:11], v60, s[68:69] offset:2048
	global_load_dwordx4 v[12:15], v60, s[68:69] offset:3072
	s_branch .LprepZ_ldd0
.LprepZ_ctx0:
	global_load_dwordx4 v[0:3], v60, s[72:73]
	global_load_dwordx4 v[4:7], v60, s[72:73] offset:1024
	global_load_dwordx4 v[8:11], v60, s[72:73] offset:2048
	global_load_dwordx4 v[12:15], v60, s[72:73] offset:3072
.LprepZ_ldd0:
.LprepZ_loop:
	v_cmp_ne_u32_e32 vcc, v65, v68
	s_nop 4
	s_cbranch_vccz .LprepZ_same
	global_load_dwordx4 v[38:41], v65, s[14:15]
	global_load_dwordx4 v[42:45], v65, s[14:15] offset:1024
	global_load_dwordx4 v[46:49], v65, s[14:15] offset:2048
	global_load_dwordx4 v[50:53], v65, s[14:15] offset:3072
	v_add_u32_e32 v59, 0x1000, v65
	v_mov_b32_e32 v68, v65
	global_load_dwordx4 v[88:91], v59, s[14:15]
	global_load_dwordx4 v[92:95], v59, s[14:15] offset:1024
	global_load_dwordx4 v[96:99], v59, s[14:15] offset:2048
	global_load_dwordx4 v[100:103], v59, s[14:15] offset:3072
	s_waitcnt vmcnt(0)
	v_pk_add_f32 v[88:89], v[88:89], 1.0 op_sel_hi:[1,0]
	v_pk_add_f32 v[90:91], v[90:91], 1.0 op_sel_hi:[1,0]
	v_pk_add_f32 v[92:93], v[92:93], 1.0 op_sel_hi:[1,0]
	v_pk_add_f32 v[94:95], v[94:95], 1.0 op_sel_hi:[1,0]
	v_pk_add_f32 v[96:97], v[96:97], 1.0 op_sel_hi:[1,0]
	v_pk_add_f32 v[98:99], v[98:99], 1.0 op_sel_hi:[1,0]
	v_pk_add_f32 v[100:101], v[100:101], 1.0 op_sel_hi:[1,0]
	v_pk_add_f32 v[102:103], v[102:103], 1.0 op_sel_hi:[1,0]
.LprepZ_same:
	s_waitcnt vmcnt(0)
	v_pk_mul_f32 v[60:61], v[0:1], v[0:1]
	v_pk_mul_f32 v[62:63], v[2:3], v[2:3]
	v_pk_fma_f32 v[60:61], v[4:5], v[4:5], v[60:61]
	v_pk_fma_f32 v[62:63], v[6:7], v[6:7], v[62:63]
	v_pk_fma_f32 v[60:61], v[8:9], v[8:9], v[60:61]
	v_pk_fma_f32 v[62:63], v[10:11], v[10:11], v[62:63]
	v_pk_fma_f32 v[60:61], v[12:13], v[12:13], v[60:61]
	v_pk_fma_f32 v[62:63], v[14:15], v[14:15], v[62:63]
	s_nop 0
	v_pk_add_f32 v[60:61], v[60:61], v[62:63]
	s_nop 1
	v_add_f32_e32 v60, v60, v61
	s_nop 1
	v_add_f32_dpp v60, v60, v60 quad_perm:[1,0,3,2] row_mask:0xf bank_mask:0xf bound_ctrl:1
	s_nop 1
	v_add_f32_dpp v60, v60, v60 quad_perm:[2,3,0,1] row_mask:0xf bank_mask:0xf bound_ctrl:1
	s_nop 1
	v_add_f32_dpp v60, v60, v60 row_half_mirror row_mask:0xf bank_mask:0xf bound_ctrl:1
	s_nop 1
	v_add_f32_dpp v60, v60, v60 row_mirror row_mask:0xf bank_mask:0xf bound_ctrl:1
	s_nop 1
	v_readlane_b32 s10, v60, 0
	v_readlane_b32 s11, v60, 16
	v_readlane_b32 s7, v60, 32
	v_readlane_b32 vcc_lo, v60, 48
	s_nop 3
	v_mov_b32_e32 v62, s10
	v_add_f32_e32 v62, s11, v62
	v_add_f32_e32 v62, s7, v62
	v_add_f32_e32 v62, vcc_lo, v62
	v_fmamk_f32 v62, v62, 0x3a800000, v66
	s_nop 0
	v_cmp_gt_f32_e32 vcc, 0x800000, v62
	v_mul_f32_e32 v60, 0x4b800000, v62
	s_nop 1
	v_cndmask_b32_e32 v62, v62, v60, vcc
	v_rsq_f32_e32 v62, v62
	s_nop 1
	v_mul_f32_e32 v60, 0x45800000, v62
	v_cndmask_b32_e32 v56, v62, v60, vcc
	s_nop 0
	v_pk_mul_f32 v[22:23], v[0:1], v[56:57] op_sel_hi:[1,0]
	v_pk_mul_f32 v[24:25], v[2:3], v[56:57] op_sel_hi:[1,0]
	v_pk_mul_f32 v[26:27], v[4:5], v[56:57] op_sel_hi:[1,0]
	v_pk_mul_f32 v[28:29], v[6:7], v[56:57] op_sel_hi:[1,0]
	v_pk_mul_f32 v[30:31], v[8:9], v[56:57] op_sel_hi:[1,0]
	v_pk_mul_f32 v[32:33], v[10:11], v[56:57] op_sel_hi:[1,0]
	v_pk_mul_f32 v[34:35], v[12:13], v[56:57] op_sel_hi:[1,0]
	v_pk_mul_f32 v[36:37], v[14:15], v[56:57] op_sel_hi:[1,0]
	v_pk_mul_f32 v[22:23], v[72:73], v[22:23]
	v_pk_mul_f32 v[24:25], v[74:75], v[24:25]
	v_pk_mul_f32 v[26:27], v[76:77], v[26:27]
	v_pk_mul_f32 v[28:29], v[78:79], v[28:29]
	v_pk_mul_f32 v[30:31], v[80:81], v[30:31]
	v_pk_mul_f32 v[32:33], v[82:83], v[32:33]
	v_pk_mul_f32 v[34:35], v[84:85], v[34:35]
	v_pk_mul_f32 v[36:37], v[86:87], v[36:37]
	v_add_u32_e32 v21, s6, v21
	s_nop 1
	v_readfirstlane_b32 s7, v21
	s_nop 3
	s_cmpk_lt_i32 s7, 0x4200
	s_cbranch_scc0 .LprepZ_nonext
	v_and_b32_e32 v59, 0xffffff80, v21
	v_and_b32_e32 v61, 0x7f, v21
	v_cmp_lt_i32_e32 vcc, 0x3fff, v59
	v_lshrrev_b32_e32 v62, 13, v59
	v_and_b32_e32 v63, 0x1fff, v59
	v_add_u32_e32 v62, 0, v62
	v_lshl_or_b32 v63, v62, 13, v63
	v_add_u32_e32 v64, 0xffffc000, v21
	v_lshrrev_b32_e32 v64, 8, v64
	v_add_u32_e32 v64, 0, v64
	v_lshlrev_b32_e32 v64, 8, v64
	v_and_b32_e32 v56, 0x80, v21
	v_or_b32_e32 v64, v64, v56
	v_cndmask_b32_e32 v63, v63, v64, vcc
	v_mov_b32_e32 v56, 4
	v_cndmask_b32_e32 v62, v62, v56, vcc
	v_add_u32_e32 v63, v63, v61
	v_lshl_add_u32 v60, v63, 12, v67
	v_add_u32_e32 v62, 0, v62
	v_mul_u32_u24_e32 v62, 0x3000, v62
	v_add_u32_e32 v65, v62, v67
	s_cbranch_vccnz .LprepZ_ctx1
	global_load_dwordx4 v[0:3], v60, s[68:69]
	global_load_dwordx4 v[4:7], v60, s[68:69] offset:1024
	global_load_dwordx4 v[8:11], v60, s[68:69] offset:2048
	global_load_dwordx4 v[12:15], v60, s[68:69] offset:3072
	s_branch .LprepZ_ldd1

.LprepZ_ldd1:
.LprepZ_nonext:
	v_pk_fma_f32 v[22:23], v[22:23], v[88:89], v[38:39]
	v_pk_fma_f32 v[24:25], v[24:25], v[90:91], v[40:41]
	v_pk_fma_f32 v[26:27], v[26:27], v[92:93], v[42:43]
	v_pk_fma_f32 v[28:29], v[28:29], v[94:95], v[44:45]
	v_pk_fma_f32 v[30:31], v[30:31], v[96:97], v[46:47]
	v_pk_fma_f32 v[32:33], v[32:33], v[98:99], v[48:49]
	v_pk_fma_f32 v[34:35], v[34:35], v[100:101], v[50:51]
	v_pk_fma_f32 v[36:37], v[36:37], v[102:103], v[52:53]
	v_cvt_pk_bf16_f32 v60, v22, v23
	v_cvt_pk_bf16_f32 v61, v24, v25
	s_nop 0
	global_store_dwordx2 v[70:71], v[60:61], off offset:-1024
	v_cvt_pk_bf16_f32 v62, v26, v27
	v_cvt_pk_bf16_f32 v63, v28, v29
	s_nop 0
	global_store_dwordx2 v[70:71], v[62:63], off offset:-512
	v_cvt_pk_bf16_f32 v60, v30, v31
	v_cvt_pk_bf16_f32 v61, v32, v33
	s_nop 0
	global_store_dwordx2 v[70:71], v[60:61], off offset:0
	v_cvt_pk_bf16_f32 v62, v34, v35
	v_cvt_pk_bf16_f32 v63, v36, v37
	s_nop 0
	global_store_dwordx2 v[70:71], v[62:63], off offset:512
	s_nop 1
	v_lshl_add_u64 v[70:71], v[70:71], 0, s[8:9]
	s_cmpk_lt_i32 s7, 0x4200
	s_cbranch_scc1 .LprepZ_loop
	s_branch .LBB0_153

.LBB0_1714:
	v_readlane_b32 s12, v180, 25
	v_readlane_b32 s13, v180, 26
	v_readlane_b32 s1, v180, 9
	v_readlane_b32 s10, v180, 15
	v_cndmask_b32_e64 v0, 0, 1, s[12:13]
	v_readlane_b32 s11, v180, 16
	v_readfirstlane_b32 s0, v0
	s_add_i32 s8, s1, s0
	s_cmp_gt_u32 s8, 3
	s_cselect_b64 s[0:1], -1, 0
	s_or_b64 s[0:1], s[10:11], s[0:1]
	s_and_b64 vcc, exec, s[0:1]
	s_cbranch_vccnz .LBB0_1723
	v_readlane_b32 s0, v180, 17
	v_mov_b32_e32 v2, v104
	s_lshl_b32 s0, s0, 2
	v_ashrrev_i32_e32 v0, 6, v2
	v_add_u32_e32 v48, s0, v0
	s_movk_i32 s1, 0x4200
	v_cmp_gt_i32_e32 vcc, s1, v48
	s_and_saveexec_b64 s[20:21], vcc
	s_cbranch_execz .LBB0_1722
	v_lshlrev_b32_e32 v1, 2, v2
	v_and_b32_e32 v4, 0xfc, v1
	v_and_b32_e32 v1, 64, v110
	v_add_u32_e32 v1, 64, v1
	v_xor_b32_e32 v3, 32, v110
	v_cmp_lt_i32_e32 vcc, v3, v1
	v_readlane_b32 s40, v182, 3
	v_readlane_b32 s56, v183, 1
	v_cndmask_b32_e32 v3, v110, v3, vcc
	v_lshlrev_b32_e32 v49, 2, v3
	v_xor_b32_e32 v3, 16, v110
	v_cmp_lt_i32_e32 vcc, v3, v1
	v_readlane_b32 s10, v182, 19
	s_cmp_eq_u32 s8, 0
	v_cndmask_b32_e32 v3, v110, v3, vcc
	v_lshlrev_b32_e32 v50, 2, v3
	v_xor_b32_e32 v3, 8, v110
	v_cmp_lt_i32_e32 vcc, v3, v1
	v_readlane_b32 s41, v182, 4
	v_readlane_b32 s44, v182, 7
	v_cndmask_b32_e32 v3, v110, v3, vcc
	v_lshlrev_b32_e32 v51, 2, v3
	v_xor_b32_e32 v3, 4, v110
	v_cmp_lt_i32_e32 vcc, v3, v1
	v_readlane_b32 s45, v182, 8
	v_readlane_b32 s68, v183, 13
	v_cndmask_b32_e32 v3, v110, v3, vcc
	v_readlane_b32 s69, v183, 14
	v_readlane_b32 s11, v182, 20
	v_lshlrev_b32_e32 v52, 2, v3
	v_xor_b32_e32 v3, 2, v110
	s_cselect_b32 s25, s41, s69
	s_cselect_b32 s24, s40, s68
	s_cselect_b32 s37, s45, s11
	s_cselect_b32 s36, s44, s10
	s_lshl_b32 s6, s8, 10
	v_cmp_lt_i32_e32 vcc, v3, v1
	v_readlane_b32 s52, v182, 15
	s_lshl_b64 s[10:11], s[6:7], 2
	v_cndmask_b32_e32 v3, v110, v3, vcc
	v_readlane_b32 s53, v182, 16
	s_add_u32 s10, s52, s10
	v_lshlrev_b32_e32 v53, 2, v3
	v_xor_b32_e32 v3, 1, v110
	s_addc_u32 s11, s53, s11
	v_cmp_lt_i32_e32 vcc, v3, v1
	s_and_b64 s[12:13], s[12:13], exec
	s_cselect_b32 s6, 0, 2
	v_cndmask_b32_e32 v1, v110, v3, vcc
	v_lshlrev_b32_e32 v54, 2, v1
	v_ashrrev_i32_e32 v1, 31, v0
	s_ashr_i32 s1, s0, 31
	v_lshl_add_u64 v[0:1], v[0:1], 0, s[0:1]
	v_readlane_b32 s57, v183, 2
	v_readlane_b32 s58, v183, 3
	v_readlane_b32 s59, v183, 4
	v_readlane_b32 s60, v183, 5
	v_readlane_b32 s61, v183, 6
	v_readlane_b32 s62, v183, 7
	v_readlane_b32 s63, v183, 8
	v_readlane_b32 s64, v183, 9
	v_readlane_b32 s65, v183, 10
	v_readlane_b32 s66, v183, 11
	v_readlane_b32 s67, v183, 12
	v_readlane_b32 s70, v183, 15
	v_readlane_b32 s71, v183, 16
	v_lshlrev_b64 v[0:1], 11, v[0:1]
	v_and_b32_e32 v2, 63, v2
	v_readlane_b32 s0, v181, 58
	v_readlane_b32 s48, v182, 11
	v_readlane_b32 s50, v182, 13
	v_readlane_b32 s51, v182, 14
	v_readlane_b32 s54, v182, 17
	v_readlane_b32 s55, v182, 18
	v_readlane_b32 s22, v183, 63
	v_readlane_b32 s56, v183, 19
	v_readlane_b32 s52, v181, 60
	v_readlane_b32 s12, v182, 1
	v_lshlrev_b32_e32 v68, 2, v4
	v_or_b32_e32 v6, 0x100, v4
	v_or_b32_e32 v8, 0x200, v4
	v_or_b32_e32 v10, 0x300, v4
	v_lshl_or_b32 v0, v2, 3, v0
	v_readlane_b32 s1, v181, 59
	s_mov_b32 s48, s5
	v_readlane_b32 s50, v180, 0
	v_readlane_b32 s23, v182, 0
	v_readlane_b32 s55, v181, 63
	v_readlane_b32 s54, v181, 62
	v_readlane_b32 s58, v183, 21
	v_readlane_b32 s59, v183, 22
	v_readlane_b32 s64, v183, 27
	v_readlane_b32 s65, v183, 28
	v_readlane_b32 s68, v183, 31
	v_readlane_b32 s69, v183, 32
	v_readlane_b32 s53, v181, 61
	v_readlane_b32 s13, v182, 2
	s_mul_i32 s8, s8, 5
	v_lshl_add_u64 v[24:25], s[10:11], 0, v[68:69]
	v_lshl_add_u64 v[26:27], s[0:1], 0, v[0:1]
	s_mov_b64 s[38:39], 0
	v_lshlrev_b32_e32 v28, 2, v4
	v_lshlrev_b32_e32 v30, 2, v6
	v_lshlrev_b32_e32 v32, 2, v8
	v_lshlrev_b32_e32 v34, 2, v10
	v_readlane_b32 s42, v182, 5
	v_readlane_b32 s43, v182, 6
	v_readlane_b32 s46, v182, 9
	v_readlane_b32 s47, v182, 10
	v_readlane_b32 s49, v182, 12
	v_readlane_b32 s51, v180, 1
	v_readlane_b32 s57, v183, 20
	v_readlane_b32 s60, v183, 23
	v_readlane_b32 s61, v183, 24
	v_readlane_b32 s62, v183, 25
	v_readlane_b32 s63, v183, 26
	v_readlane_b32 s66, v183, 29
	v_readlane_b32 s67, v183, 30
	v_readlane_b32 s70, v183, 33
	v_readlane_b32 s71, v183, 34
	v_mov_b32_e32 v56, v28
	v_mov_b32_e32 v60, v26
	v_mov_b32_e32 v61, v27
	global_load_dwordx4 v[72:75], v[24:25], off
	global_load_dwordx4 v[76:79], v[24:25], off offset:1024
	global_load_dwordx4 v[80:83], v[24:25], off offset:2048
	global_load_dwordx4 v[84:87], v[24:25], off offset:3072
	v_mov_b32_e32 v57, -1
	v_and_b32_e32 v49, 0xffffff80, v48
	v_and_b32_e32 v51, 0x7f, v48
	v_cmp_lt_i32_e32 vcc, 0x3fff, v49
	v_lshrrev_b32_e32 v52, 13, v49
	v_and_b32_e32 v53, 0x1fff, v49
	v_add_u32_e32 v52, s6, v52
	v_lshl_or_b32 v53, v52, 13, v53
	v_add_u32_e32 v54, 0xffffc000, v48
	v_lshrrev_b32_e32 v54, 8, v54
	v_add_u32_e32 v54, s6, v54
	v_lshlrev_b32_e32 v54, 8, v54
	v_and_b32_e32 v58, 0x80, v48
	v_or_b32_e32 v54, v54, v58
	v_cndmask_b32_e32 v53, v53, v54, vcc
	v_mov_b32_e32 v58, 4
	v_cndmask_b32_e32 v52, v52, v58, vcc
	v_add_u32_e32 v53, v53, v51
	v_lshl_add_u32 v50, v53, 12, v56
	v_add_u32_e32 v52, s8, v52
	v_mul_u32_u24_e32 v52, 0x3000, v52
	v_add_u32_e32 v55, v52, v56
	s_cbranch_vccnz .LprepT_ctx0
	global_load_dwordx4 v[0:3], v50, s[24:25]
	global_load_dwordx4 v[4:7], v50, s[24:25] offset:1024
	global_load_dwordx4 v[8:11], v50, s[24:25] offset:2048
	global_load_dwordx4 v[12:15], v50, s[24:25] offset:3072
	s_branch .LprepT_ldd0
.LprepT_ctx0:
	global_load_dwordx4 v[0:3], v50, s[36:37]
	global_load_dwordx4 v[4:7], v50, s[36:37] offset:1024
	global_load_dwordx4 v[8:11], v50, s[36:37] offset:2048
	global_load_dwordx4 v[12:15], v50, s[36:37] offset:3072
.LprepT_ldd0:
.LprepT_loop:
	v_cmp_ne_u32_e32 vcc, v55, v57
	s_nop 4
	s_cbranch_vccz .LprepT_same
	global_load_dwordx4 v[32:35], v55, s[12:13]
	global_load_dwordx4 v[36:39], v55, s[12:13] offset:1024
	global_load_dwordx4 v[40:43], v55, s[12:13] offset:2048
	global_load_dwordx4 v[44:47], v55, s[12:13] offset:3072
	v_add_u32_e32 v49, 0x1000, v55
	v_mov_b32_e32 v57, v55
	global_load_dwordx4 v[88:91], v49, s[12:13]
	global_load_dwordx4 v[92:95], v49, s[12:13] offset:1024
	global_load_dwordx4 v[96:99], v49, s[12:13] offset:2048
	global_load_dwordx4 v[100:103], v49, s[12:13] offset:3072
	s_waitcnt vmcnt(0)
	v_pk_add_f32 v[88:89], v[88:89], 1.0 op_sel_hi:[1,0]
	v_pk_add_f32 v[90:91], v[90:91], 1.0 op_sel_hi:[1,0]
	v_pk_add_f32 v[92:93], v[92:93], 1.0 op_sel_hi:[1,0]
	v_pk_add_f32 v[94:95], v[94:95], 1.0 op_sel_hi:[1,0]
	v_pk_add_f32 v[96:97], v[96:97], 1.0 op_sel_hi:[1,0]
	v_pk_add_f32 v[98:99], v[98:99], 1.0 op_sel_hi:[1,0]
	v_pk_add_f32 v[100:101], v[100:101], 1.0 op_sel_hi:[1,0]
	v_pk_add_f32 v[102:103], v[102:103], 1.0 op_sel_hi:[1,0]
.LprepT_same:
	s_waitcnt vmcnt(0)
	v_pk_mul_f32 v[50:51], v[0:1], v[0:1]
	v_pk_mul_f32 v[52:53], v[2:3], v[2:3]
	v_pk_fma_f32 v[50:51], v[4:5], v[4:5], v[50:51]
	v_pk_fma_f32 v[52:53], v[6:7], v[6:7], v[52:53]
	v_pk_fma_f32 v[50:51], v[8:9], v[8:9], v[50:51]
	v_pk_fma_f32 v[52:53], v[10:11], v[10:11], v[52:53]
	v_pk_fma_f32 v[50:51], v[12:13], v[12:13], v[50:51]
	v_pk_fma_f32 v[52:53], v[14:15], v[14:15], v[52:53]
	s_nop 0
	v_pk_add_f32 v[50:51], v[50:51], v[52:53]
	s_nop 1
	v_add_f32_e32 v50, v50, v51
	s_nop 1
	v_add_f32_dpp v50, v50, v50 quad_perm:[1,0,3,2] row_mask:0xf bank_mask:0xf bound_ctrl:1
	s_nop 1
	v_add_f32_dpp v50, v50, v50 quad_perm:[2,3,0,1] row_mask:0xf bank_mask:0xf bound_ctrl:1
	s_nop 1
	v_add_f32_dpp v50, v50, v50 row_half_mirror row_mask:0xf bank_mask:0xf bound_ctrl:1
	s_nop 1
	v_add_f32_dpp v50, v50, v50 row_mirror row_mask:0xf bank_mask:0xf bound_ctrl:1
	s_nop 1
	v_readlane_b32 s0, v50, 0
	v_readlane_b32 s1, v50, 16
	v_readlane_b32 s9, v50, 32
	v_readlane_b32 vcc_lo, v50, 48
	s_nop 3
	v_mov_b32_e32 v52, s0
	v_add_f32_e32 v52, s1, v52
	v_add_f32_e32 v52, s9, v52
	v_add_f32_e32 v52, vcc_lo, v52
	v_fmamk_f32 v52, v52, 0x3a800000, v111
	s_nop 0
	v_cmp_gt_f32_e32 vcc, 0x800000, v52
	v_mul_f32_e32 v50, 0x4b800000, v52
	s_nop 1
	v_cndmask_b32_e32 v52, v52, v50, vcc
	v_rsq_f32_e32 v52, v52
	s_nop 1
	v_mul_f32_e32 v50, 0x45800000, v52
	v_cndmask_b32_e32 v58, v52, v50, vcc
	s_nop 0
	v_pk_mul_f32 v[16:17], v[0:1], v[58:59] op_sel_hi:[1,0]
	v_pk_mul_f32 v[18:19], v[2:3], v[58:59] op_sel_hi:[1,0]
	v_pk_mul_f32 v[20:21], v[4:5], v[58:59] op_sel_hi:[1,0]
	v_pk_mul_f32 v[22:23], v[6:7], v[58:59] op_sel_hi:[1,0]
	v_pk_mul_f32 v[24:25], v[8:9], v[58:59] op_sel_hi:[1,0]
	v_pk_mul_f32 v[26:27], v[10:11], v[58:59] op_sel_hi:[1,0]
	v_pk_mul_f32 v[28:29], v[12:13], v[58:59] op_sel_hi:[1,0]
	v_pk_mul_f32 v[30:31], v[14:15], v[58:59] op_sel_hi:[1,0]
	v_pk_mul_f32 v[16:17], v[72:73], v[16:17]
	v_pk_mul_f32 v[18:19], v[74:75], v[18:19]
	v_pk_mul_f32 v[20:21], v[76:77], v[20:21]
	v_pk_mul_f32 v[22:23], v[78:79], v[22:23]
	v_pk_mul_f32 v[24:25], v[80:81], v[24:25]
	v_pk_mul_f32 v[26:27], v[82:83], v[26:27]
	v_pk_mul_f32 v[28:29], v[84:85], v[28:29]
	v_pk_mul_f32 v[30:31], v[86:87], v[30:31]
	v_readlane_b32 s0, v180, 20
	s_nop 3
	v_add_u32_e32 v48, s0, v48
	s_nop 1
	v_readfirstlane_b32 s9, v48
	s_nop 3
	s_cmpk_lt_i32 s9, 0x4200
	s_cbranch_scc0 .LprepT_nonext
	v_and_b32_e32 v49, 0xffffff80, v48
	v_and_b32_e32 v51, 0x7f, v48
	v_cmp_lt_i32_e32 vcc, 0x3fff, v49
	v_lshrrev_b32_e32 v52, 13, v49
	v_and_b32_e32 v53, 0x1fff, v49
	v_add_u32_e32 v52, s6, v52
	v_lshl_or_b32 v53, v52, 13, v53
	v_add_u32_e32 v54, 0xffffc000, v48
	v_lshrrev_b32_e32 v54, 8, v54
	v_add_u32_e32 v54, s6, v54
	v_lshlrev_b32_e32 v54, 8, v54
	v_and_b32_e32 v58, 0x80, v48
	v_or_b32_e32 v54, v54, v58
	v_cndmask_b32_e32 v53, v53, v54, vcc
	v_mov_b32_e32 v58, 4
	v_cndmask_b32_e32 v52, v52, v58, vcc
	v_add_u32_e32 v53, v53, v51
	v_lshl_add_u32 v50, v53, 12, v56
	v_add_u32_e32 v52, s8, v52
	v_mul_u32_u24_e32 v52, 0x3000, v52
	v_add_u32_e32 v55, v52, v56
	s_cbranch_vccnz .LprepT_ctx1
	global_load_dwordx4 v[0:3], v50, s[24:25]
	global_load_dwordx4 v[4:7], v50, s[24:25] offset:1024
	global_load_dwordx4 v[8:11], v50, s[24:25] offset:2048
	global_load_dwordx4 v[12:15], v50, s[24:25] offset:3072
	s_branch .LprepT_ldd1

.LprepT_ldd1:
.LprepT_nonext:
	v_pk_fma_f32 v[16:17], v[16:17], v[88:89], v[32:33]
	v_pk_fma_f32 v[18:19], v[18:19], v[90:91], v[34:35]
	v_pk_fma_f32 v[20:21], v[20:21], v[92:93], v[36:37]
	v_pk_fma_f32 v[22:23], v[22:23], v[94:95], v[38:39]
	v_pk_fma_f32 v[24:25], v[24:25], v[96:97], v[40:41]
	v_pk_fma_f32 v[26:27], v[26:27], v[98:99], v[42:43]
	v_pk_fma_f32 v[28:29], v[28:29], v[100:101], v[44:45]
	v_pk_fma_f32 v[30:31], v[30:31], v[102:103], v[46:47]
	v_readlane_b32 s0, v180, 22
	v_readlane_b32 s1, v180, 23
	v_cvt_pk_bf16_f32 v50, v16, v17
	v_cvt_pk_bf16_f32 v51, v18, v19
	s_nop 0
	global_store_dwordx2 v[60:61], v[50:51], off offset:-1024
	v_cvt_pk_bf16_f32 v52, v20, v21
	v_cvt_pk_bf16_f32 v53, v22, v23
	s_nop 0
	global_store_dwordx2 v[60:61], v[52:53], off offset:-512
	v_cvt_pk_bf16_f32 v50, v24, v25
	v_cvt_pk_bf16_f32 v51, v26, v27
	s_nop 0
	global_store_dwordx2 v[60:61], v[50:51], off offset:0
	v_cvt_pk_bf16_f32 v52, v28, v29
	v_cvt_pk_bf16_f32 v53, v30, v31
	s_nop 0
	global_store_dwordx2 v[60:61], v[52:53], off offset:512
	s_nop 1
	v_lshl_add_u64 v[60:61], v[60:61], 0, s[0:1]
	s_cmpk_lt_i32 s9, 0x4200
	s_cbranch_scc1 .LprepT_loop
	s_branch .LBB0_1722
